# two grid barriers replaced by counter flags (scan phase after local-state phase; cumulative-forget phase after forget-logit pass) with write-through producer stores
# speedup vs baseline: 1.0128x; 1.0128x over previous
; __device__ __forceinline__ unsigned xb_add(unsigned* p, unsigned v) { return __hip_atomic_fetch_add(p, v, __ATOMIC_RELAXED, __HIP_MEMORY_SCOPE_AGENT); }
; __device__ __forceinline__ void xcd_barrier(const XcdBarrier& b) {
;     ...
;             __builtin_amdgcn_fence(__ATOMIC_ACQUIRE, "agent");
;             xb_add(&bar[XB_XGEN(b.x)], 1u);
;             asm volatile("s_waitcnt vmcnt(0)" ::: "memory");
.LBB0_82:
	s_or_b64 exec, exec, s[18:19]
	s_mov_b64 s[18:19], exec
	v_mbcnt_lo_u32_b32 v0, s18, 0
	v_mbcnt_hi_u32_b32 v0, s19, v0
	v_cmp_eq_u32_e32 vcc, 0, v0
	s_waitcnt vmcnt(0)
	buffer_inv sc1
	s_and_saveexec_b64 s[20:21], vcc
	s_cbranch_execz .LBB0_84
	s_bcnt1_i32_b64 s3, s[18:19]
	v_mov_b32_e32 v0, 0
	v_mov_b32_e32 v1, s3
.LBB0_84:
	s_or_b64 exec, exec, s[20:21]
	s_waitcnt vmcnt(0)

; __device__ __forceinline__ unsigned xb_add(unsigned* p, unsigned v) { return __hip_atomic_fetch_add(p, v, __ATOMIC_RELAXED, __HIP_MEMORY_SCOPE_AGENT); }
; __device__ __forceinline__ void xcd_barrier(const XcdBarrier& b) {
;     ...
;             __builtin_amdgcn_fence(__ATOMIC_ACQUIRE, "agent");
;             xb_add(&bar[XB_XGEN(b.x)], 1u);
;             asm volatile("s_waitcnt vmcnt(0)" ::: "memory");
.LBB0_145:
	s_or_b64 exec, exec, s[18:19]
	s_mov_b64 s[18:19], exec
	v_mbcnt_lo_u32_b32 v0, s18, 0
	v_mbcnt_hi_u32_b32 v0, s19, v0
	v_cmp_eq_u32_e32 vcc, 0, v0
	s_waitcnt vmcnt(0)
	buffer_inv sc1
	s_and_saveexec_b64 s[20:21], vcc
	s_cbranch_execz .LBB0_147
	s_bcnt1_i32_b64 s3, s[18:19]
	v_mov_b32_e32 v0, 0
	v_mov_b32_e32 v1, s3
.LBB0_147:
	s_or_b64 exec, exec, s[20:21]
	s_waitcnt vmcnt(0)

; __device__ __forceinline__ unsigned xb_add(unsigned* p, unsigned v) { return __hip_atomic_fetch_add(p, v, __ATOMIC_RELAXED, __HIP_MEMORY_SCOPE_AGENT); }
; __device__ __forceinline__ void xcd_barrier(const XcdBarrier& b) {
;     ...
;             __builtin_amdgcn_fence(__ATOMIC_ACQUIRE, "agent");
;             xb_add(&bar[XB_XGEN(b.x)], 1u);
;             asm volatile("s_waitcnt vmcnt(0)" ::: "memory");
.LBB0_213:
	s_or_b64 exec, exec, s[18:19]
	s_mov_b64 s[18:19], exec
	v_mbcnt_lo_u32_b32 v0, s18, 0
	v_mbcnt_hi_u32_b32 v0, s19, v0
	v_cmp_eq_u32_e32 vcc, 0, v0
	s_waitcnt vmcnt(0)
	buffer_inv sc1
	s_and_saveexec_b64 s[22:23], vcc
	s_cbranch_execz .LBB0_215
	s_bcnt1_i32_b64 s5, s[18:19]
	v_mov_b32_e32 v0, 0
	v_mov_b32_e32 v1, s5
.LBB0_215:
	s_or_b64 exec, exec, s[22:23]
	s_waitcnt vmcnt(0)

; #define LAS __attribute__((address_space(3)))
; #define HB() asm volatile("s_waitcnt lgkmcnt(0)\n\ts_barrier" ::: "memory")
; template <bool PC> __device__ __forceinline__ void hgrn_unit(LAS unsigned char* lds, int unit, const bf16* P0, const float* lbp, const float* ong, float* Lst, const float* Sst, float* Dtot, bf16* MIX) {
;     ...
;           for (int t = 0; t < 8; ++t) { const float f = __uint_as_float(nf[t] << 16); const float sg = sigmf(f); const float fg = lb + (1.f - lb) * sg; lf[t] = __builtin_amdgcn_logf(fg); ky[t] = 1.f - fg;
;               if (PC) qv[t] = __uint_as_float(nq[t] << 16); }
;         }
;         const v4u cv = nv, ga = ng;
;         if (step < 7) HG_LOAD(step + 1);
; #pragma unroll
;         for (int t = 1; t < 8; ++t) lf[t] += lf[t - 1];
;         { const int s = tid >> 4, c16 = tid & 15; *(LAS v4u*)(lds + HL_V + s * RS + c16 * 16) = cv; }
;         float pre, cl;
;         { const float T = lf[7]; const float p1 = __shfl_up(T, 16), p2 = __shfl_up(T, 32), p3 = __shfl_up(T, 48);
;           pre = (tq >= 1 ? p1 : 0.f) + (tq >= 2 ? p2 : 0.f) + (tq >= 3 ? p3 : 0.f);
;           const float s2 = T + __shfl_xor(T, 16); cl = s2 + __shfl_xor(s2, 32); }
;         const float ecl = __builtin_amdgcn_exp2f(cl);
;         { unsigned kw[4];
; #pragma unroll
;           for (int t = 0; t < 8; t += 2) { const float c0 = pre + lf[t], c1 = pre + lf[t + 1];
;               const float k0 = ky[t] * __builtin_amdgcn_exp2f(-c0), k1 = ky[t + 1] * __builtin_amdgcn_exp2f(-c1);
;               kw[t >> 1] = pk2(k0 * ecl, k1 * ecl);
;               if (PC) { const unsigned kk = pk2(k0, k1), qq = pk2(qv[t] * __builtin_amdgcn_exp2f(c0), qv[t + 1] * __builtin_amdgcn_exp2f(c1));
;                   *(LAS unsigned short*)(lds + HL_KT + (8 * tq + t) * RS + k * 2) = (unsigned short)(kk & 0xffffu);
;                   *(LAS unsigned short*)(lds + HL_KT + (8 * tq + t + 1) * RS + k * 2) = (unsigned short)(kk >> 16);
;                   *(LAS unsigned short*)(lds + HL_QT + (8 * tq + t) * RS + k * 2) = (unsigned short)(qq & 0xffffu);
;                   *(LAS unsigned short*)(lds + HL_QT + (8 * tq + t + 1) * RS + k * 2) = (unsigned short)(qq >> 16); } }
;           *(LAS v4u*)(lds + HL_KE + k * 80 + tq * 16) = (v4u){kw[0], kw[1], kw[2], kw[3]}; }
;         if (tq == 0) DEC[k] = ecl;
;         sumlog += cl;
;         HB();
.LBB0_222:
	v_lshlrev_b32_e32 v86, 16, v86
	v_lshlrev_b32_e32 v87, 16, v87
	v_mul_f32_e32 v86, 0xbfb8aa3b, v86
	v_mul_f32_e32 v87, 0xbfb8aa3b, v87
	v_exp_f32_e32 v86, v86
	v_exp_f32_e32 v87, v87
	v_lshlrev_b32_e32 v80, 16, v80
	v_lshlrev_b32_e32 v84, 16, v84
	v_mul_f32_e32 v80, 0xbfb8aa3b, v80
	v_add_f32_e32 v86, 1.0, v86
	v_add_f32_e32 v87, 1.0, v87
	v_mul_f32_e32 v84, 0xbfb8aa3b, v84
	v_lshlrev_b32_e32 v83, 16, v83
	v_exp_f32_e32 v80, v80
	v_rcp_f32_e32 v86, v86
	v_rcp_f32_e32 v87, v87
	v_lshlrev_b32_e32 v85, 16, v85
	v_exp_f32_e32 v89, v84
	v_mul_f32_e32 v83, 0xbfb8aa3b, v83
	v_mul_f32_e32 v85, 0xbfb8aa3b, v85
	v_exp_f32_e32 v83, v83
	v_exp_f32_e32 v88, v85
	v_add_f32_e32 v80, 1.0, v80
	v_pk_fma_f32 v[84:85], v[50:51], v[86:87], v[48:49]
	v_add_f32_e32 v87, 1.0, v89
	v_rcp_f32_e32 v89, v80
	v_lshlrev_b32_e32 v80, 16, v81
	v_add_f32_e32 v83, 1.0, v83
	v_mul_f32_e32 v80, 0xbfb8aa3b, v80
	v_add_f32_e32 v86, 1.0, v88
	v_rcp_f32_e32 v88, v83
	v_exp_f32_e32 v83, v80
	v_lshlrev_b32_e32 v80, 16, v82
	v_mul_f32_e32 v80, 0xbfb8aa3b, v80
	v_exp_f32_e32 v90, v80
	v_rcp_f32_e32 v86, v86
	v_rcp_f32_e32 v87, v87
	v_add_f32_e32 v82, 1.0, v83
	v_add_f32_e32 v83, 1.0, v90
	v_rcp_f32_e32 v82, v82
	v_rcp_f32_e32 v83, v83
	v_log_f32_e32 v92, v84
	v_log_f32_e32 v93, v85
	v_pk_fma_f32 v[86:87], v[50:51], v[86:87], v[48:49]
	v_pk_fma_f32 v[80:81], v[50:51], v[88:89], v[48:49]
	v_log_f32_e32 v94, v86
	v_log_f32_e32 v95, v87
	v_log_f32_e32 v96, v80
	v_log_f32_e32 v97, v81
	v_pk_add_f32 v[88:89], v[80:81], 1.0 op_sel_hi:[1,0] neg_lo:[1,0] neg_hi:[1,0]
	v_pk_fma_f32 v[80:81], v[50:51], v[82:83], v[48:49]
	ds_write_b128 v42, v[32:35]
	v_log_f32_e32 v82, v80
	v_pk_add_f32 v[90:91], v[80:81], 1.0 op_sel_hi:[1,0] neg_lo:[1,0] neg_hi:[1,0]
	v_add_f32_e32 v80, v92, v93
	v_log_f32_e32 v83, v81
	v_add_f32_e32 v81, v94, v80
	v_add_f32_e32 v93, v95, v81
	v_add_f32_e32 v94, v96, v93
	v_add_f32_e32 v95, v97, v94
	v_add_f32_e32 v96, v82, v95
	v_add_f32_e32 v97, v83, v96
	ds_bpermute_b32 v83, v63, v97
	ds_bpermute_b32 v82, v47, v97
	ds_bpermute_b32 v32, v53, v97
	ds_bpermute_b32 v33, v62, v97
	v_pk_add_f32 v[84:85], v[84:85], 1.0 op_sel_hi:[1,0] neg_lo:[1,0] neg_hi:[1,0]
	s_waitcnt lgkmcnt(3)
	v_add_f32_e32 v35, v97, v83
	s_waitcnt lgkmcnt(2)
	v_cndmask_b32_e64 v34, v82, 0, s[36:37]
	ds_bpermute_b32 v82, v64, v35
	s_waitcnt lgkmcnt(2)
	v_cndmask_b32_e64 v32, 0, v32, s[38:39]
	v_add_f32_e32 v32, v34, v32
	s_waitcnt lgkmcnt(1)
	v_cndmask_b32_e64 v33, 0, v33, s[40:41]
	v_add_f32_e32 v98, v32, v33
	s_waitcnt lgkmcnt(0)
	v_add_f32_e32 v33, v35, v82
	v_add_f32_e32 v34, v92, v98
	v_add_f32_e32 v35, v80, v98
	v_exp_f32_e64 v34, -v34
	v_exp_f32_e64 v35, -v35
	v_exp_f32_e32 v32, v33
	v_add_f32_e32 v80, v81, v98
	v_add_f32_e32 v81, v93, v98
	v_exp_f32_e64 v82, -v80
	v_exp_f32_e64 v83, -v81
	v_pk_mul_f32 v[34:35], v[84:85], v[34:35]
	v_pk_add_f32 v[86:87], v[86:87], 1.0 op_sel_hi:[1,0] neg_lo:[1,0] neg_hi:[1,0]
	v_pk_mul_f32 v[34:35], v[32:33], v[34:35] op_sel_hi:[0,1]
	v_cvt_pk_bf16_f32 v80, v34, v35
	v_pk_mul_f32 v[34:35], v[86:87], v[82:83]
	v_add_f32_e32 v82, v96, v98
	v_pk_mul_f32 v[34:35], v[32:33], v[34:35] op_sel_hi:[0,1]
	v_cvt_pk_bf16_f32 v81, v34, v35
	v_add_f32_e32 v34, v94, v98
	v_add_f32_e32 v35, v95, v98
	v_exp_f32_e64 v34, -v34
	v_exp_f32_e64 v35, -v35
	v_add_f32_e32 v83, v97, v98
	v_exp_f32_e64 v84, -v82
	v_exp_f32_e64 v85, -v83
	v_pk_mul_f32 v[34:35], v[88:89], v[34:35]
	s_nop 0
	v_pk_mul_f32 v[34:35], v[32:33], v[34:35] op_sel_hi:[0,1]
	v_cvt_pk_bf16_f32 v82, v34, v35
	v_pk_mul_f32 v[34:35], v[90:91], v[84:85]
	s_nop 0
	v_pk_mul_f32 v[34:35], v[32:33], v[34:35] op_sel_hi:[0,1]
	v_cvt_pk_bf16_f32 v83, v34, v35
	v_add_u32_e32 v34, v65, v52
	ds_write_b128 v34, v[80:83] offset:26112
	s_and_saveexec_b64 s[18:19], s[36:37]
	ds_write_b32 v69, v32 offset:40960
	s_or_b64 exec, exec, s[18:19]
	s_waitcnt lgkmcnt(0)
	s_barrier
; #define LAS __attribute__((address_space(3)))
; template <bool PC> __device__ __forceinline__ void hgrn_unit(LAS unsigned char* lds, int unit, const bf16* P0, const float* lbp, const float* ong, float* Lst, const float* Sst, float* Dtot, bf16* MIX) {
;     ...
;         const bf16x8 xv = trfrag((const LAS char*)(lds + HL_V + (8 * g + q4) * RS + (16 * wave + 4 * p4) * 2), 4 * RS);
;         bf16x8 xs[4], yq[2][4], ysc[2], yk[8]; float dcv[8];
;         if (PC) {
; #pragma unroll
;             for (int tb = 0; tb < 2; ++tb) ysc[tb] = *(const LAS bf16x8*)(lds + HL_SC + (16 * tb + li) * 80 + g * 16);
; #pragma unroll
;             for (int ks = 0; ks < 4; ++ks) { xs[ks] = trfrag((const LAS char*)(lds + HL_S + (32 * ks + 8 * g + q4) * RS + (16 * wave + 4 * p4) * 2), 4 * RS);
; #pragma unroll
;                 for (int tb = 0; tb < 2; ++tb) yq[tb][ks] = *(const LAS bf16x8*)(lds + HL_QT + (16 * tb + li) * RS + (32 * ks + 8 * g) * 2); }
;         }
; #pragma unroll
;         for (int kb = 0; kb < 8; ++kb) { dcv[kb] = DEC[16 * kb + li]; yk[kb] = *(const LAS bf16x8*)(lds + HL_KE + (16 * kb + li) * 80 + g * 16); }
;         __builtin_amdgcn_sched_barrier(0);
;         if (PC) {
;             f32x4 o[2];
; #pragma unroll
;             for (int tb = 0; tb < 2; ++tb) o[tb] = __builtin_amdgcn_mfma_f32_16x16x32_bf16(xv, ysc[tb], (f32x4){0.f, 0.f, 0.f, 0.f}, 0, 0, 0);
; #pragma unroll
;             for (int ks = 0; ks < 4; ++ks)
; #pragma unroll
;                 for (int tb = 0; tb < 2; ++tb) o[tb] = __builtin_amdgcn_mfma_f32_16x16x32_bf16(xs[ks], yq[tb][ks], o[tb], 0, 0, 0);
; #pragma unroll
;             for (int tb = 0; tb < 2; ++tb) *(LAS f32x4*)(lds + HL_OUT + ((16 * tb + li) * 132 + 16 * wave + 4 * g) * 4) = o[tb];
;         }
; #pragma unroll
;         for (int kb = 0; kb < 8; ++kb) S[kb] = __builtin_amdgcn_mfma_f32_16x16x32_bf16(xv, yk[kb], S[kb] * dcv[kb], 0, 0, 0);
;         HB();
;         if (PC) {
; #pragma unroll
;             for (int kb = 0; kb < 8; ++kb) *(LAS v2u*)(lds + HL_S + (16 * kb + li) * RS + (16 * wave + 4 * g) * 2) = (v2u){pk2(S[kb][0], S[kb][1]), pk2(S[kb][2], S[kb][3])};
;             const int t = tid >> 4, vg = tid & 15;
;             const f32x4 o0 = *(const LAS f32x4*)(lds + HL_OUT + (t * 132 + 8 * vg) * 4), o1 = *(const LAS f32x4*)(lds + HL_OUT + (t * 132 + 8 * vg + 4) * 4);
	v_add_u32_e32 v32, 0xa000, v66
	ds_read_b64_tr_b16 v[80:81], v70
	ds_read_b64_tr_b16 v[82:83], v70 offset:1088
	ds_read2_b32 v[34:35], v32 offset1:16
	ds_read_b128 v[84:87], v71 offset:26112
	ds_read_b128 v[88:91], v71 offset:27392
	ds_read2_b32 v[116:117], v32 offset0:32 offset1:48
	ds_read_b128 v[92:95], v71 offset:28672
	ds_read_b128 v[96:99], v71 offset:29952
	ds_read2_b32 v[118:119], v32 offset0:64 offset1:80
	ds_read_b128 v[100:103], v71 offset:31232
	ds_read_b128 v[104:107], v71 offset:32512
	ds_read2_b32 v[120:121], v32 offset0:96 offset1:112
	ds_read_b128 v[108:111], v71 offset:33792
	ds_read_b128 v[112:115], v71 offset:35072
	s_waitcnt lgkmcnt(11)
	v_mov_b32_e32 v32, v35
	v_pk_mul_f32 v[18:19], v[18:19], v[32:33] op_sel_hi:[1,0]
	v_pk_mul_f32 v[16:17], v[16:17], v[32:33] op_sel_hi:[1,0]
	s_waitcnt lgkmcnt(8)
	v_mov_b32_e32 v32, v117
	v_pk_mul_f32 v[14:15], v[14:15], v[32:33] op_sel_hi:[1,0]
	v_pk_mul_f32 v[12:13], v[12:13], v[32:33] op_sel_hi:[1,0]
	s_waitcnt lgkmcnt(5)
	v_mov_b32_e32 v32, v119
	v_pk_mul_f32 v[10:11], v[10:11], v[32:33] op_sel_hi:[1,0]
	v_pk_mul_f32 v[8:9], v[8:9], v[32:33] op_sel_hi:[1,0]
	s_waitcnt lgkmcnt(2)
	v_mov_b32_e32 v32, v121
	v_pk_mul_f32 v[26:27], v[26:27], v[34:35] op_sel_hi:[1,0]
	v_pk_mul_f32 v[24:25], v[24:25], v[34:35] op_sel_hi:[1,0]
	v_pk_mul_f32 v[22:23], v[22:23], v[116:117] op_sel_hi:[1,0]
	v_pk_mul_f32 v[20:21], v[20:21], v[116:117] op_sel_hi:[1,0]
	v_pk_mul_f32 v[6:7], v[6:7], v[118:119] op_sel_hi:[1,0]
	v_pk_mul_f32 v[4:5], v[4:5], v[118:119] op_sel_hi:[1,0]
	v_pk_mul_f32 v[2:3], v[2:3], v[120:121] op_sel_hi:[1,0]
	v_pk_mul_f32 v[0:1], v[0:1], v[120:121] op_sel_hi:[1,0]
	v_pk_mul_f32 v[30:31], v[30:31], v[32:33] op_sel_hi:[1,0]
	v_pk_mul_f32 v[28:29], v[28:29], v[32:33] op_sel_hi:[1,0]
	v_mfma_f32_16x16x32_bf16 v[24:27], v[80:83], v[84:87], v[24:27]
	s_waitcnt lgkmcnt(0)
	s_barrier
	s_add_i32 s5, s5, 32
	v_add_f32_e32 v45, v45, v33
	v_mfma_f32_16x16x32_bf16 v[16:19], v[80:83], v[88:91], v[16:19]
	s_cmpk_eq_i32 s5, 0x100
	v_mfma_f32_16x16x32_bf16 v[20:23], v[80:83], v[92:95], v[20:23]
	v_mfma_f32_16x16x32_bf16 v[12:15], v[80:83], v[96:99], v[12:15]
	v_mfma_f32_16x16x32_bf16 v[4:7], v[80:83], v[100:103], v[4:7]
	v_mfma_f32_16x16x32_bf16 v[8:11], v[80:83], v[104:107], v[8:11]
	s_waitcnt lgkmcnt(1)
	v_mfma_f32_16x16x32_bf16 v[0:3], v[80:83], v[108:111], v[0:3]
	s_waitcnt lgkmcnt(0)
	v_mfma_f32_16x16x32_bf16 v[28:31], v[80:83], v[112:115], v[28:31]
	s_cbranch_scc0 .LBB0_220
	s_ashr_i32 s43, s42, 31
	s_lshl_b64 s[14:15], s[42:43], 16
	s_add_u32 s14, s44, s14
	s_addc_u32 s15, s45, s15
	v_ashrrev_i32_e32 v47, 31, v46
	v_lshl_add_u64 v[32:33], v[46:47], 2, s[14:15]
	v_mov_b32_e32 v53, v43
	v_lshl_add_u64 v[32:33], v[32:33], 0, v[52:53]
	v_lshlrev_b32_e32 v42, 9, v61
	v_lshl_add_u64 v[32:33], v[32:33], 0, v[42:43]
	s_movk_i32 s5, 0x2000
	global_store_dwordx4 v[32:33], v[24:27], off sc1
	s_nop 1
	v_add_co_u32_e32 v24, vcc, s5, v32
	s_nop 1
	v_addc_co_u32_e32 v25, vcc, 0, v33, vcc
	global_store_dwordx4 v[24:25], v[16:19], off sc1
	s_nop 1
	v_add_co_u32_e32 v16, vcc, s75, v32
	s_nop 1
	v_addc_co_u32_e32 v17, vcc, 0, v33, vcc
	global_store_dwordx4 v[16:17], v[20:23], off sc1
	v_add_co_u32_e32 v16, vcc, s76, v32
	s_nop 1
	v_addc_co_u32_e32 v17, vcc, 0, v33, vcc
	global_store_dwordx4 v[16:17], v[12:15], off sc1
	s_nop 1
	v_add_co_u32_e32 v12, vcc, 0x8000, v32
	s_nop 1
	v_addc_co_u32_e32 v13, vcc, 0, v33, vcc
	global_store_dwordx4 v[12:13], v[4:7], off sc1
	s_nop 1
	v_add_co_u32_e32 v4, vcc, 0xa000, v32
	s_nop 1
	v_addc_co_u32_e32 v5, vcc, 0, v33, vcc
	global_store_dwordx4 v[4:5], v[8:11], off sc1
	v_add_co_u32_e32 v4, vcc, 0xc000, v32
	s_nop 1
	v_addc_co_u32_e32 v5, vcc, 0, v33, vcc
	global_store_dwordx4 v[4:5], v[0:3], off sc1
	s_nop 1
	v_add_co_u32_e32 v0, vcc, 0xe000, v32
	s_nop 1
	v_addc_co_u32_e32 v1, vcc, 0, v33, vcc
	global_store_dwordx4 v[0:1], v[28:31], off sc1
	s_and_saveexec_b64 s[18:19], s[36:37]
	s_cbranch_execz .LBB0_218
	v_exp_f32_e32 v2, v45
	v_lshl_add_u32 v0, s42, 7, v44
	v_ashrrev_i32_e32 v1, 31, v0
	v_lshl_add_u64 v[0:1], v[0:1], 2, s[0:1]
	global_store_dword v[0:1], v2, off sc1
	s_branch .LBB0_218

; __device__ __forceinline__ void weight_copy_items(const Args& a, LAS unsigned char* lds, int lo, int hi, int G) {
;     ...
;     for (int it = lo + (int)blockIdx.x * NWAVES + wave; it < hi; it += G * NWAVES) {
;         int r = it;
;         if (r < I0) { const int kb = r / 96, nb = r % 96; transpose_item(a.in[6], D, N0, (bf16*)(ws + WS_W0IN), 32 * nb, 64 * kb, 32 * nb, scr, lane); continue; } r -= I0;
; __global__ void __launch_bounds__(NTHR, 2) fwd_megakernel(Args args) {
;     ...
;     for (int u = blockIdx.x; u < 256; u += G) hgrn_unit<false>(lds, u, P0, args.in[5], args.in[7], (float*)(ws + WS_LST), nullptr, (float*)(ws + WS_DTOT), MIX);
;     for (int u = blockIdx.x; u < 512; u += G) pool_unit(lds, u, P0, (const bf16*)(ws + WS_POOLW), args.in[9], MIX);
;     weight_copy_items(args, lds, 16 * 96 + 32, 16 * 96 + 32 + 16 * 32 + 16 * 129 + 16 * 32, G);
.LBB0_261:
	s_and_saveexec_b64 s[100:101], s[92:93]
	s_cbranch_execz .Lp3_sig_done
	s_mov_b32 s98, 0
	s_mov_b32 s99, s91
.Lp3_cnt:
	s_cmpk_gt_i32 s99, 0xff
	s_cbranch_scc1 .Lp3_cnt_done
	s_add_i32 s98, s98, 1
	s_add_i32 s99, s99, s6
	s_branch .Lp3_cnt
.Lp3_cnt_done:
	v_mov_b32_e32 v250, 0
	v_mov_b32_e32 v251, s98
	global_atomic_add v250, v251, s[10:11] offset:3328
.Lp3_sig_done:
	s_mov_b64 exec, s[100:101]
	v_readlane_b32 s0, v249, 3
	s_addk_i32 s0, 0x620
	s_add_u32 s24, s10, 0x1300000
	s_addc_u32 s25, s11, 0
	s_add_u32 s70, s10, 0xa00000
	v_mov_b32_e32 v0, v216
	s_addc_u32 s71, s11, 0
	s_add_u32 s74, s10, 0x800000
	v_ashrrev_i32_e32 v1, 6, v0
	v_add_u32_e32 v18, s0, v1
	s_movk_i32 s0, 0x1230
	s_addc_u32 s75, s11, 0
	v_cmp_gt_i32_e32 vcc, s0, v18
	s_and_saveexec_b64 s[0:1], vcc
	s_cbranch_execz .LBB0_346
	v_and_b32_e32 v19, 31, v0
	v_bfe_u32 v20, v0, 5, 1
	v_bfe_u32 v22, v0, 3, 3
	v_lshlrev_b32_e32 v0, 3, v0
	v_lshl_add_u32 v4, v1, 14, 0
	v_lshlrev_b32_e32 v1, 2, v19
	v_mul_u32_u24_e32 v2, 0x84, v20
	v_and_b32_e32 v10, 56, v0
	v_add3_u32 v21, v4, v1, v2
	v_mul_u32_u24_e32 v5, 0x84, v10
	v_mov_b32_e32 v1, 0
	v_lshlrev_b32_e32 v0, 1, v10
	v_lshlrev_b32_e32 v6, 2, v22
	v_lshl_add_u64 v[2:3], s[24:25], 0, v[0:1]
	v_add3_u32 v23, v4, v5, v6
	v_lshl_add_u64 v[4:5], s[70:71], 0, v[0:1]
	v_lshl_add_u64 v[6:7], s[74:75], 0, v[0:1]
	v_lshl_add_u64 v[8:9], s[48:49], 0, v[0:1]
	v_mov_b32_e32 v0, 0xfffdfa00
	v_or_b32_e32 v24, 8, v22
	v_or_b32_e32 v25, 16, v22
	v_or_b32_e32 v26, 24, v22
	v_lshl_add_u32 v27, v18, 5, v0
	s_lshl_b32 s50, s4, 5
	v_lshlrev_b32_e32 v28, 1, v18
	s_lshl_b32 s51, s4, 1
	v_lshlrev_b32_e32 v29, 4, v18
	s_lshl_b32 s54, s4, 4
	s_mov_b64 s[38:39], 0
	s_movk_i32 s55, 0x3000
	v_lshlrev_b32_e32 v10, 1, v10
	v_add_u32_e32 v30, 0x400, v21
	v_add_u32_e32 v31, 0x800, v21
	v_add_u32_e32 v32, 0xc00, v21
	v_add_u32_e32 v33, 0x1000, v21
	v_add_u32_e32 v34, 0x1400, v21
	v_add_u32_e32 v35, 0x1800, v21
	s_waitcnt vmcnt(8)
	v_add_u32_e32 v36, 0x1c00, v21
	s_branch .LBB0_264

; #define GSYNC() do { xcd_barrier(xbar); xcd_barrier(xbar); } while (0)
; #define GSYNC() xcd_barrier(xbar)
; #define REP(p) for (int rep_ = 0; rep_ < (((PROBE_MASK >> (p)) & 1) ? 2 : 1); ++rep_)
; __device__ __forceinline__ void hgrn_scan_phase(const float* __restrict__ Lst, const float* __restrict__ Dtot, float* __restrict__ Sst, int G) {
;     int tid = threadIdx.x; asm volatile("" : "+v"(tid));
;     for (int e = blockIdx.x * NTHR + tid; e < 8 * 16384; e += G * NTHR) {
; __global__ void __launch_bounds__(NTHR, 2) fwd_megakernel(Args args) {
;     ...
;     GSYNC(); }
;     REP(4) { hgrn_scan_phase((const float*)(ws + WS_LST), (const float*)(ws + WS_DTOT), (float*)(ws + WS_SST), G);
.LBB0_346:
	s_or_b64 exec, exec, s[0:1]
	s_waitcnt vmcnt(0)
	s_and_saveexec_b64 s[100:101], s[92:93]
	s_cbranch_execz .Lp4_polled
	v_mov_b32_e32 v250, 0
.Lp4_poll:
	global_load_dword v251, v250, s[10:11] offset:3328 sc1
	s_waitcnt vmcnt(0)
	v_cmp_gt_u32_e32 vcc, 0x100, v251
	s_nop 1
	s_cbranch_vccz .Lp4_pollend
	s_sleep 1
	s_branch .Lp4_poll
.Lp4_pollend:
	buffer_inv sc1
	s_waitcnt vmcnt(0)
.Lp4_polled:
	s_mov_b64 exec, s[100:101]
	s_waitcnt lgkmcnt(0)
	v_mov_b32_e32 v0, v216
	s_barrier
	s_mov_b32 s0, 0x20000
	v_lshl_add_u32 v10, s91, 9, v0
	v_cmp_gt_i32_e32 vcc, s0, v10
	s_and_saveexec_b64 s[0:1], vcc
	s_cbranch_execz .LBB0_403
	s_lshl_b32 s14, s91, 9
	s_lshl_b32 s5, s6, 9
	v_add_u16_e32 v11, s14, v0
	s_mov_b64 s[50:51], 0
	s_mov_b64 s[18:19], 0x80000

; __device__ __forceinline__ unsigned xb_add(unsigned* p, unsigned v) { return __hip_atomic_fetch_add(p, v, __ATOMIC_RELAXED, __HIP_MEMORY_SCOPE_AGENT); }
; __device__ __forceinline__ void xcd_barrier(const XcdBarrier& b) {
;     ...
;             __builtin_amdgcn_fence(__ATOMIC_ACQUIRE, "agent");
;             xb_add(&bar[XB_XGEN(b.x)], 1u);
;             asm volatile("s_waitcnt vmcnt(0)" ::: "memory");
.LBB0_452:
	s_or_b64 exec, exec, s[18:19]
	s_mov_b64 s[18:19], exec
	v_mbcnt_lo_u32_b32 v0, s18, 0
	v_mbcnt_hi_u32_b32 v0, s19, v0
	v_cmp_eq_u32_e32 vcc, 0, v0
	s_waitcnt vmcnt(0)
	buffer_inv sc1
	s_and_saveexec_b64 s[36:37], vcc
	s_cbranch_execz .LBB0_454
	s_bcnt1_i32_b64 s5, s[18:19]
	v_mov_b32_e32 v0, 0
	v_mov_b32_e32 v1, s5
.LBB0_454:
	s_or_b64 exec, exec, s[36:37]
	s_waitcnt vmcnt(0)

; __device__ __forceinline__ unsigned xb_add(unsigned* p, unsigned v) { return __hip_atomic_fetch_add(p, v, __ATOMIC_RELAXED, __HIP_MEMORY_SCOPE_AGENT); }
; __device__ __forceinline__ void xcd_barrier(const XcdBarrier& b) {
;     ...
;             __builtin_amdgcn_fence(__ATOMIC_ACQUIRE, "agent");
;             xb_add(&bar[XB_XGEN(b.x)], 1u);
;             asm volatile("s_waitcnt vmcnt(0)" ::: "memory");
.LBB0_524:
	s_or_b64 exec, exec, s[18:19]
	s_mov_b64 s[18:19], exec
	v_mbcnt_lo_u32_b32 v0, s18, 0
	v_mbcnt_hi_u32_b32 v0, s19, v0
	v_cmp_eq_u32_e32 vcc, 0, v0
	s_waitcnt vmcnt(0)
	buffer_inv sc1
	s_and_saveexec_b64 s[38:39], vcc
	s_cbranch_execz .LBB0_526
	s_bcnt1_i32_b64 s5, s[18:19]
	v_mov_b32_e32 v0, 0
	v_mov_b32_e32 v1, s5
.LBB0_526:
	s_or_b64 exec, exec, s[38:39]
	s_waitcnt vmcnt(0)

; __device__ __forceinline__ unsigned xb_add(unsigned* p, unsigned v) { return __hip_atomic_fetch_add(p, v, __ATOMIC_RELAXED, __HIP_MEMORY_SCOPE_AGENT); }
; __device__ __forceinline__ void xcd_barrier(const XcdBarrier& b) {
;     ...
;             __builtin_amdgcn_fence(__ATOMIC_ACQUIRE, "agent");
;             xb_add(&bar[XB_XGEN(b.x)], 1u);
;             asm volatile("s_waitcnt vmcnt(0)" ::: "memory");
.LBB0_614:
	s_or_b64 exec, exec, s[18:19]
	s_mov_b64 s[18:19], exec
	v_mbcnt_lo_u32_b32 v0, s18, 0
	v_mbcnt_hi_u32_b32 v0, s19, v0
	v_cmp_eq_u32_e32 vcc, 0, v0
	s_waitcnt vmcnt(0)
	buffer_inv sc1
	s_and_saveexec_b64 s[36:37], vcc
	s_cbranch_execz .LBB0_616
	s_bcnt1_i32_b64 s5, s[18:19]
	v_mov_b32_e32 v0, 0
	v_mov_b32_e32 v1, s5
.LBB0_616:
	s_or_b64 exec, exec, s[36:37]
	s_waitcnt vmcnt(0)

; __device__ __forceinline__ void fl_phase(const bf16* H, const bf16* Wfl, const float* bfv, const float* rowss, const float* biasp, float* logf, int G) {
;     ...
;     for (int rb = blockIdx.x + G * wave; rb < M / 16; rb += G * NWAVES) {
;         const bf16* ap = H + (size_t)(16 * rb + li) * D + 8 * g; const bf16* bp = Wfl + (size_t)li * D + 8 * g;
;         f32x4 acc = (f32x4){0.f, 0.f, 0.f, 0.f};
; #pragma unroll 8
;         for (int ks = 0; ks < 32; ++ks) { const bf16x8 a = *(const bf16x8*)(ap + 32 * ks), b = *(const bf16x8*)(bp + 32 * ks);
;             acc = __builtin_amdgcn_mfma_f32_16x16x32_bf16(a, b, acc, 0, 0, 0); }
.LBB0_619:
	v_ashrrev_i32_e32 v15, 31, v14
	v_lshlrev_b64 v[0:1], 11, v[14:15]
	v_lshl_add_u64 v[4:5], v[12:13], 0, v[0:1]
	s_mov_b64 s[18:19], 0
	v_mov_b32_e32 v0, 0
	v_mov_b32_e32 v1, v9
	v_mov_b32_e32 v2, v9
	v_mov_b32_e32 v3, v9
	v_ashrrev_i32_e32 v192, 9, v44
	s_movk_i32 s98, 0x1100
	v_mad_i32_i24 v192, v192, s98, v46
	v_ashrrev_i32_e32 v193, 31, v192
	v_lshl_add_u64 v[192:193], v[192:193], 2, s[44:45]
	v_lshlrev_b32_e32 v194, 4, v44
	v_or_b32_e32 v194, v194, v47
	v_ashrrev_i32_e32 v195, 31, v194
	v_lshl_add_u64 v[194:195], v[194:195], 2, s[42:43]
	global_load_dword v186, v[10:11], off
	global_load_dword v187, v[192:193], off
	global_load_dwordx4 v[188:191], v[194:195], off
	v_add_co_u32_e32 v6, vcc, 0x1800000, v4
	s_nop 1
	v_addc_co_u32_e32 v7, vcc, 0, v5, vcc
	v_add_co_u32_e32 v28, vcc, 0x1200000, v16
	s_nop 1
	v_addc_co_u32_e32 v29, vcc, 0, v17, vcc
	global_load_dwordx4 v[58:61], v[6:7], off
	global_load_dwordx4 v[62:65], v[28:29], off
	global_load_dwordx4 v[66:69], v[6:7], off offset:64
	global_load_dwordx4 v[70:73], v[28:29], off offset:64
	global_load_dwordx4 v[74:77], v[6:7], off offset:128
	global_load_dwordx4 v[78:81], v[28:29], off offset:128
	global_load_dwordx4 v[82:85], v[6:7], off offset:192
	global_load_dwordx4 v[86:89], v[28:29], off offset:192
	global_load_dwordx4 v[90:93], v[6:7], off offset:256
	global_load_dwordx4 v[94:97], v[28:29], off offset:256
	global_load_dwordx4 v[98:101], v[6:7], off offset:320
	global_load_dwordx4 v[102:105], v[28:29], off offset:320
	global_load_dwordx4 v[106:109], v[6:7], off offset:384
	global_load_dwordx4 v[110:113], v[28:29], off offset:384
	global_load_dwordx4 v[114:117], v[6:7], off offset:448
	global_load_dwordx4 v[118:121], v[28:29], off offset:448
	global_load_dwordx4 v[122:125], v[6:7], off offset:512
	global_load_dwordx4 v[126:129], v[28:29], off offset:512
	global_load_dwordx4 v[130:133], v[6:7], off offset:576
	global_load_dwordx4 v[134:137], v[28:29], off offset:576
	global_load_dwordx4 v[138:141], v[6:7], off offset:640
	global_load_dwordx4 v[142:145], v[28:29], off offset:640
	global_load_dwordx4 v[146:149], v[6:7], off offset:704
	global_load_dwordx4 v[150:153], v[28:29], off offset:704
	global_load_dwordx4 v[154:157], v[6:7], off offset:768
	global_load_dwordx4 v[158:161], v[28:29], off offset:768
	global_load_dwordx4 v[162:165], v[6:7], off offset:832
	global_load_dwordx4 v[166:169], v[28:29], off offset:832
	global_load_dwordx4 v[170:173], v[6:7], off offset:896
	global_load_dwordx4 v[174:177], v[28:29], off offset:896
	global_load_dwordx4 v[178:181], v[6:7], off offset:960
	global_load_dwordx4 v[182:185], v[28:29], off offset:960
	s_waitcnt vmcnt(30)
	v_mfma_f32_16x16x32_bf16 v[0:3], v[58:61], v[62:65], v[0:3]
	global_load_dwordx4 v[58:61], v[6:7], off offset:1024
	global_load_dwordx4 v[62:65], v[28:29], off offset:1024
	s_waitcnt vmcnt(30)
	v_mfma_f32_16x16x32_bf16 v[0:3], v[66:69], v[70:73], v[0:3]
	global_load_dwordx4 v[66:69], v[6:7], off offset:1088
	global_load_dwordx4 v[70:73], v[28:29], off offset:1088
	s_waitcnt vmcnt(30)
	v_mfma_f32_16x16x32_bf16 v[0:3], v[74:77], v[78:81], v[0:3]
	global_load_dwordx4 v[74:77], v[6:7], off offset:1152
	global_load_dwordx4 v[78:81], v[28:29], off offset:1152
	s_waitcnt vmcnt(30)
	v_mfma_f32_16x16x32_bf16 v[0:3], v[82:85], v[86:89], v[0:3]
	global_load_dwordx4 v[82:85], v[6:7], off offset:1216
	global_load_dwordx4 v[86:89], v[28:29], off offset:1216
	s_waitcnt vmcnt(30)
	v_mfma_f32_16x16x32_bf16 v[0:3], v[90:93], v[94:97], v[0:3]
	global_load_dwordx4 v[90:93], v[6:7], off offset:1280
	global_load_dwordx4 v[94:97], v[28:29], off offset:1280
	s_waitcnt vmcnt(30)
	v_mfma_f32_16x16x32_bf16 v[0:3], v[98:101], v[102:105], v[0:3]
	global_load_dwordx4 v[98:101], v[6:7], off offset:1344
	global_load_dwordx4 v[102:105], v[28:29], off offset:1344
	s_waitcnt vmcnt(30)
	v_mfma_f32_16x16x32_bf16 v[0:3], v[106:109], v[110:113], v[0:3]
	global_load_dwordx4 v[106:109], v[6:7], off offset:1408
	global_load_dwordx4 v[110:113], v[28:29], off offset:1408
	s_waitcnt vmcnt(30)
	v_mfma_f32_16x16x32_bf16 v[0:3], v[114:117], v[118:121], v[0:3]
	global_load_dwordx4 v[114:117], v[6:7], off offset:1472
	global_load_dwordx4 v[118:121], v[28:29], off offset:1472
	s_waitcnt vmcnt(30)
	v_mfma_f32_16x16x32_bf16 v[0:3], v[122:125], v[126:129], v[0:3]
	global_load_dwordx4 v[122:125], v[6:7], off offset:1536
	global_load_dwordx4 v[126:129], v[28:29], off offset:1536
	s_waitcnt vmcnt(30)
	v_mfma_f32_16x16x32_bf16 v[0:3], v[130:133], v[134:137], v[0:3]
	global_load_dwordx4 v[130:133], v[6:7], off offset:1600
	global_load_dwordx4 v[134:137], v[28:29], off offset:1600
	s_waitcnt vmcnt(30)
	v_mfma_f32_16x16x32_bf16 v[0:3], v[138:141], v[142:145], v[0:3]
	global_load_dwordx4 v[138:141], v[6:7], off offset:1664
	global_load_dwordx4 v[142:145], v[28:29], off offset:1664
	s_waitcnt vmcnt(30)
	v_mfma_f32_16x16x32_bf16 v[0:3], v[146:149], v[150:153], v[0:3]
	global_load_dwordx4 v[146:149], v[6:7], off offset:1728
	global_load_dwordx4 v[150:153], v[28:29], off offset:1728
	s_waitcnt vmcnt(30)
	v_mfma_f32_16x16x32_bf16 v[0:3], v[154:157], v[158:161], v[0:3]
	global_load_dwordx4 v[154:157], v[6:7], off offset:1792
	global_load_dwordx4 v[158:161], v[28:29], off offset:1792
	s_waitcnt vmcnt(30)
	v_mfma_f32_16x16x32_bf16 v[0:3], v[162:165], v[166:169], v[0:3]
	global_load_dwordx4 v[162:165], v[6:7], off offset:1856
	global_load_dwordx4 v[166:169], v[28:29], off offset:1856
	s_waitcnt vmcnt(30)
	v_mfma_f32_16x16x32_bf16 v[0:3], v[170:173], v[174:177], v[0:3]
	global_load_dwordx4 v[170:173], v[6:7], off offset:1920
	global_load_dwordx4 v[174:177], v[28:29], off offset:1920
	s_waitcnt vmcnt(30)
; __device__ __forceinline__ void fl_phase(const bf16* H, const bf16* Wfl, const float* bfv, const float* rowss, const float* biasp, float* logf, int G) {
;     ...
; #pragma unroll 8
;         for (int ks = 0; ks < 32; ++ks) { const bf16x8 a = *(const bf16x8*)(ap + 32 * ks), b = *(const bf16x8*)(bp + 32 * ks);
;             acc = __builtin_amdgcn_mfma_f32_16x16x32_bf16(a, b, acc, 0, 0, 0); }
;         const int row = 16 * rb + 4 * g, bb = row >> 13, t = row & 8191; const float bias = bfv[li] + biasp[bb * 4352 + 4096 + li];
;         const f32x4 rq = *(const f32x4*)(rowss + row);
;         f32x4 o;
; #pragma unroll
;         for (int r = 0; r < 4; ++r) { const float z = acc[r] * __builtin_amdgcn_rsqf(rq[r] * (1.0f / 1024.0f) + EPSN) + bias; o[r] = fminf(z, 0.f) - log1pf(__expf(-fabsf(z))); }
	v_mfma_f32_16x16x32_bf16 v[0:3], v[178:181], v[182:185], v[0:3]
	global_load_dwordx4 v[178:181], v[6:7], off offset:1984
	global_load_dwordx4 v[182:185], v[28:29], off offset:1984
	s_waitcnt vmcnt(30)
	v_mfma_f32_16x16x32_bf16 v[0:3], v[58:61], v[62:65], v[0:3]
	s_waitcnt vmcnt(28)
	v_mfma_f32_16x16x32_bf16 v[0:3], v[66:69], v[70:73], v[0:3]
	s_waitcnt vmcnt(26)
	v_mfma_f32_16x16x32_bf16 v[0:3], v[74:77], v[78:81], v[0:3]
	s_waitcnt vmcnt(24)
	v_mfma_f32_16x16x32_bf16 v[0:3], v[82:85], v[86:89], v[0:3]
	s_waitcnt vmcnt(22)
	v_mfma_f32_16x16x32_bf16 v[0:3], v[90:93], v[94:97], v[0:3]
	s_waitcnt vmcnt(20)
	v_mfma_f32_16x16x32_bf16 v[0:3], v[98:101], v[102:105], v[0:3]
	s_waitcnt vmcnt(18)
	v_mfma_f32_16x16x32_bf16 v[0:3], v[106:109], v[110:113], v[0:3]
	s_waitcnt vmcnt(16)
	v_mfma_f32_16x16x32_bf16 v[0:3], v[114:117], v[118:121], v[0:3]
	s_waitcnt vmcnt(14)
	v_mfma_f32_16x16x32_bf16 v[0:3], v[122:125], v[126:129], v[0:3]
	s_waitcnt vmcnt(12)
	v_mfma_f32_16x16x32_bf16 v[0:3], v[130:133], v[134:137], v[0:3]
	s_waitcnt vmcnt(10)
	v_mfma_f32_16x16x32_bf16 v[0:3], v[138:141], v[142:145], v[0:3]
	s_waitcnt vmcnt(8)
	v_mfma_f32_16x16x32_bf16 v[0:3], v[146:149], v[150:153], v[0:3]
	s_waitcnt vmcnt(6)
	v_mfma_f32_16x16x32_bf16 v[0:3], v[154:157], v[158:161], v[0:3]
	s_waitcnt vmcnt(4)
	v_mfma_f32_16x16x32_bf16 v[0:3], v[162:165], v[166:169], v[0:3]
	s_waitcnt vmcnt(2)
	v_mfma_f32_16x16x32_bf16 v[0:3], v[170:173], v[174:177], v[0:3]
	s_waitcnt vmcnt(0)
	v_mfma_f32_16x16x32_bf16 v[0:3], v[178:181], v[182:185], v[0:3]
	v_ashrrev_i32_e32 v15, 9, v44
	v_lshlrev_b32_e32 v8, 4, v44
	s_movk_i32 s14, 0x1ffc
	v_add_u32_e32 v44, s4, v44
	v_add_u32_e32 v14, s5, v14
	v_add_f32_e32 v52, v186, v187
	v_mov_b32_e32 v4, v188
	v_mov_b32_e32 v5, v189
	v_mov_b32_e32 v6, v190
	v_mov_b32_e32 v7, v191
	v_fmamk_f32 v4, v4, 0x3a800000, v48
	v_rsq_f32_e32 v4, v4
	v_fmamk_f32 v5, v5, 0x3a800000, v48
	v_rsq_f32_e32 v5, v5
	v_fma_f32 v4, v0, v4, v52
	v_min_f32_e32 v0, 0, v4
	v_mul_f32_e64 v4, |v4|, s47
	v_exp_f32_e32 v53, v4
	v_fma_f32 v5, v1, v5, v52
	v_min_f32_e32 v1, 0, v5
	v_mul_f32_e64 v5, |v5|, s47
	v_add_f32_e32 v4, 1.0, v53
	v_add_f32_e32 v20, -1.0, v4
	v_sub_f32_e32 v21, v20, v4
	v_add_f32_e32 v21, 1.0, v21
	v_sub_f32_e32 v20, v53, v20
	v_add_f32_e32 v22, v20, v21
	v_frexp_mant_f32_e32 v20, v4
	v_exp_f32_e32 v54, v5
	v_cmp_gt_f32_e32 vcc, s49, v20
	v_cvt_f64_f32_e32 v[20:21], v4
	v_frexp_exp_i32_f64_e32 v20, v[20:21]
	v_subbrev_co_u32_e32 v20, vcc, 0, v20, vcc
	v_sub_u32_e32 v21, 0, v20
	v_add_f32_e32 v5, 1.0, v54
	v_ldexp_f32 v4, v4, v21
	v_ldexp_f32 v22, v22, v21
	v_add_f32_e32 v21, -1.0, v5
	v_sub_f32_e32 v23, v21, v5
	v_add_f32_e32 v23, 1.0, v23
	v_sub_f32_e32 v21, v54, v21
	v_add_f32_e32 v21, v21, v23
	v_frexp_mant_f32_e32 v23, v5
	v_cvt_f64_f32_e32 v[24:25], v5
	v_cmp_gt_f32_e32 vcc, s49, v23
	v_frexp_exp_i32_f64_e32 v23, v[24:25]
	v_cmp_lt_f32_e64 s[36:37], |v54|, s53
	v_subbrev_co_u32_e32 v40, vcc, 0, v23, vcc
	v_sub_u32_e32 v23, 0, v40
	v_ldexp_f32 v5, v5, v23
	v_pk_add_f32 v[24:25], v[4:5], 1.0 op_sel_hi:[1,0]
	v_ldexp_f32 v23, v21, v23
	v_pk_add_f32 v[26:27], v[24:25], -1.0 op_sel_hi:[1,0]
	v_pk_add_f32 v[32:33], v[4:5], -1.0 op_sel_hi:[1,0]
	v_pk_add_f32 v[26:27], v[4:5], v[26:27] neg_lo:[0,1] neg_hi:[0,1]
	v_pk_add_f32 v[34:35], v[32:33], 1.0 op_sel_hi:[1,0]
	v_pk_add_f32 v[26:27], v[22:23], v[26:27]
	v_pk_add_f32 v[4:5], v[4:5], v[34:35] neg_lo:[0,1] neg_hi:[0,1]
	v_pk_add_f32 v[28:29], v[24:25], v[26:27]
	v_pk_add_f32 v[4:5], v[22:23], v[4:5]
	v_rcp_f32_e32 v30, v28
	v_rcp_f32_e32 v31, v29
	v_pk_add_f32 v[22:23], v[32:33], v[4:5]
	v_pk_add_f32 v[24:25], v[28:29], v[24:25] neg_lo:[0,1] neg_hi:[0,1]
	v_pk_add_f32 v[32:33], v[22:23], v[32:33] neg_lo:[0,1] neg_hi:[0,1]
	v_pk_add_f32 v[24:25], v[26:27], v[24:25] neg_lo:[0,1] neg_hi:[0,1]
	v_pk_mul_f32 v[26:27], v[22:23], v[30:31]
	v_pk_add_f32 v[4:5], v[4:5], v[32:33] neg_lo:[0,1] neg_hi:[0,1]
	v_pk_mul_f32 v[32:33], v[28:29], v[26:27]
	v_cmp_neq_f32_e32 vcc, s51, v53
	v_pk_fma_f32 v[34:35], v[26:27], v[28:29], v[32:33] neg_lo:[0,0,1] neg_hi:[0,0,1]
	s_nop 0
	v_pk_fma_f32 v[34:35], v[26:27], v[24:25], v[34:35]
	s_nop 0
	v_pk_add_f32 v[36:37], v[32:33], v[34:35]
	s_nop 0
	v_pk_add_f32 v[38:39], v[22:23], v[36:37] neg_lo:[0,1] neg_hi:[0,1]
	v_pk_add_f32 v[32:33], v[36:37], v[32:33] neg_lo:[0,1] neg_hi:[0,1]
	v_pk_add_f32 v[22:23], v[22:23], v[38:39] neg_lo:[0,1] neg_hi:[0,1]
	s_nop 0
	v_pk_add_f32 v[22:23], v[22:23], v[36:37] neg_lo:[0,1] neg_hi:[0,1]
	s_nop 0
	v_pk_add_f32 v[4:5], v[4:5], v[22:23]
	v_pk_add_f32 v[22:23], v[32:33], v[34:35] neg_lo:[0,1] neg_hi:[0,1]
	s_nop 0
	v_pk_add_f32 v[4:5], v[22:23], v[4:5]
	s_nop 0
	v_pk_add_f32 v[22:23], v[38:39], v[4:5]
	s_nop 0
	v_pk_mul_f32 v[32:33], v[30:31], v[22:23]
	s_nop 0
	v_pk_mul_f32 v[34:35], v[28:29], v[32:33]
	s_nop 0
	v_pk_fma_f32 v[28:29], v[32:33], v[28:29], v[34:35] neg_lo:[0,0,1] neg_hi:[0,0,1]
	s_nop 0
	v_pk_fma_f32 v[24:25], v[32:33], v[24:25], v[28:29]
	v_pk_add_f32 v[28:29], v[38:39], v[22:23] neg_lo:[0,1] neg_hi:[0,1]
	s_nop 0
	v_pk_add_f32 v[4:5], v[4:5], v[28:29]
	v_pk_add_f32 v[28:29], v[34:35], v[24:25]
	s_nop 0
	v_pk_add_f32 v[36:37], v[22:23], v[28:29] neg_lo:[0,1] neg_hi:[0,1]
	v_pk_add_f32 v[34:35], v[28:29], v[34:35] neg_lo:[0,1] neg_hi:[0,1]
	v_pk_add_f32 v[22:23], v[22:23], v[36:37] neg_lo:[0,1] neg_hi:[0,1]
	s_nop 0
	v_pk_add_f32 v[22:23], v[22:23], v[28:29] neg_lo:[0,1] neg_hi:[0,1]
	s_nop 0
	v_pk_add_f32 v[4:5], v[4:5], v[22:23]
	v_pk_add_f32 v[22:23], v[34:35], v[24:25] neg_lo:[0,1] neg_hi:[0,1]
	s_nop 0
	v_pk_add_f32 v[4:5], v[22:23], v[4:5]
	v_pk_add_f32 v[22:23], v[26:27], v[32:33]
	v_pk_add_f32 v[4:5], v[36:37], v[4:5]
; __device__ __forceinline__ void fl_phase(const bf16* H, const bf16* Wfl, const float* bfv, const float* rowss, const float* biasp, float* logf, int G) {
;     ...
;         for (int r = 0; r < 4; ++r) { const float z = acc[r] * __builtin_amdgcn_rsqf(rq[r] * (1.0f / 1024.0f) + EPSN) + bias; o[r] = fminf(z, 0.f) - log1pf(__expf(-fabsf(z))); }
	v_pk_add_f32 v[24:25], v[22:23], v[26:27] neg_lo:[0,1] neg_hi:[0,1]
	v_pk_mul_f32 v[4:5], v[30:31], v[4:5]
	v_pk_add_f32 v[24:25], v[32:33], v[24:25] neg_lo:[0,1] neg_hi:[0,1]
	s_nop 0
	v_pk_add_f32 v[4:5], v[24:25], v[4:5]
	s_nop 0
	v_pk_add_f32 v[24:25], v[22:23], v[4:5]
	s_nop 0
	v_pk_add_f32 v[22:23], v[24:25], v[22:23] neg_lo:[0,1] neg_hi:[0,1]
	v_pk_mul_f32 v[32:33], v[24:25], v[24:25]
	v_pk_add_f32 v[22:23], v[4:5], v[22:23] neg_lo:[0,1] neg_hi:[0,1]
	v_ldexp_f32 v28, v24, 1
	v_ldexp_f32 v26, v22, 1
	v_pk_fma_f32 v[4:5], v[32:33], s[46:47], v[18:19] op_sel_hi:[1,0,0]
	v_ldexp_f32 v29, v25, 1
	v_ldexp_f32 v31, v23, 1
	v_pk_mul_f32 v[22:23], v[24:25], v[32:33]
	v_cvt_f32_i32_e32 v25, v40
	v_cvt_f32_i32_e32 v24, v20
	v_pk_fma_f32 v[4:5], v[32:33], v[4:5], s[48:49] op_sel_hi:[1,1,0]
	v_mov_b32_e32 v27, v31
	v_pk_mul_f32 v[32:33], v[22:23], v[4:5]
	v_pk_mul_f32 v[20:21], v[24:25], s[50:51] op_sel_hi:[1,0]
	v_pk_add_f32 v[4:5], v[28:29], v[32:33]
	v_pk_fma_f32 v[22:23], v[24:25], s[50:51], v[20:21] op_sel_hi:[1,0,1] neg_lo:[0,0,1] neg_hi:[0,0,1]
	v_pk_add_f32 v[28:29], v[4:5], v[28:29] neg_lo:[0,1] neg_hi:[0,1]
	v_pk_fma_f32 v[22:23], v[24:25], s[52:53], v[22:23] op_sel_hi:[1,0,1]
	v_pk_add_f32 v[34:35], v[32:33], v[28:29] neg_lo:[0,1] neg_hi:[0,1]
	v_mov_b32_e32 v28, v20
	v_pk_add_f32 v[32:33], v[26:27], v[34:35]
	v_mov_b32_e32 v29, v35
	v_mov_b32_e32 v30, v22
	v_mov_b32_e32 v27, v33
	v_mov_b32_e32 v35, v5
	v_pk_add_f32 v[24:25], v[20:21], v[22:23]
	v_pk_add_f32 v[28:29], v[28:29], v[30:31]
	v_pk_add_f32 v[30:31], v[26:27], v[34:35]
	v_pk_add_f32 v[34:35], v[4:5], v[32:33]
	v_mov_b32_e32 v42, v4
	v_pk_add_f32 v[26:27], v[24:25], v[34:35]
	v_mov_b32_e32 v40, v34
	v_mov_b32_e32 v41, v27
	v_mov_b32_e32 v43, v25
	v_pk_add_f32 v[40:41], v[40:41], v[42:43] neg_lo:[0,1] neg_hi:[0,1]
	v_mov_b32_e32 v36, v26
	v_mov_b32_e32 v37, v25
	v_mov_b32_e32 v38, v24
	v_mov_b32_e32 v39, v21
	v_mov_b32_e32 v42, v24
	v_mov_b32_e32 v43, v27
	v_mov_b32_e32 v21, v41
	v_pk_add_f32 v[36:37], v[36:37], v[38:39] neg_lo:[0,1] neg_hi:[0,1]
	v_mov_b32_e32 v38, v34
	v_mov_b32_e32 v39, v23
	v_pk_add_f32 v[20:21], v[42:43], v[20:21] neg_lo:[0,1] neg_hi:[0,1]
	v_pk_add_f32 v[38:39], v[38:39], v[36:37] neg_lo:[0,1] neg_hi:[0,1]
	v_mov_b32_e32 v42, v20
	v_mov_b32_e32 v43, v37
	v_mov_b32_e32 v56, v26
	v_mov_b32_e32 v57, v35
	v_mov_b32_e32 v37, v5
	v_pk_add_f32 v[42:43], v[22:23], v[42:43] neg_lo:[0,1] neg_hi:[0,1]
	v_pk_add_f32 v[36:37], v[56:57], v[36:37] neg_lo:[0,1] neg_hi:[0,1]
	v_mov_b32_e32 v23, v25
	v_pk_add_f32 v[28:29], v[28:29], v[36:37] neg_lo:[0,1] neg_hi:[0,1]
	v_pk_add_f32 v[20:21], v[22:23], v[20:21] neg_lo:[0,1] neg_hi:[0,1]
	v_pk_add_f32 v[22:23], v[30:31], v[40:41] neg_lo:[0,1] neg_hi:[0,1]
	v_pk_add_f32 v[30:31], v[38:39], v[28:29]
	v_pk_add_f32 v[24:25], v[22:23], v[20:21]
	v_mov_b32_e32 v21, v39
	v_mov_b32_e32 v23, v29
	v_pk_add_f32 v[22:23], v[20:21], v[22:23]
	v_pk_add_f32 v[4:5], v[34:35], v[4:5] neg_lo:[0,1] neg_hi:[0,1]
	v_pk_add_f32 v[22:23], v[22:23], v[42:43] neg_lo:[0,1] neg_hi:[0,1]
	v_mov_b32_e32 v28, v24
	v_mov_b32_e32 v29, v31
	v_pk_add_f32 v[4:5], v[32:33], v[4:5] neg_lo:[0,1] neg_hi:[0,1]
	v_pk_add_f32 v[28:29], v[28:29], v[22:23] neg_lo:[0,1] neg_hi:[0,1]
	v_pk_add_f32 v[4:5], v[4:5], v[22:23] neg_lo:[0,1] neg_hi:[0,1]
	v_pk_add_f32 v[20:21], v[20:21], v[28:29] neg_lo:[0,1] neg_hi:[0,1]
	s_nop 0
	v_pk_add_f32 v[4:5], v[4:5], v[20:21]
	v_pk_add_f32 v[20:21], v[30:31], v[24:25]
	s_nop 0
	v_pk_add_f32 v[22:23], v[26:27], v[20:21]
	s_nop 0
	v_pk_add_f32 v[24:25], v[22:23], v[26:27] neg_lo:[0,1] neg_hi:[0,1]
	s_nop 0
	v_pk_add_f32 v[20:21], v[20:21], v[24:25] neg_lo:[0,1] neg_hi:[0,1]
	s_nop 0
	v_pk_add_f32 v[4:5], v[4:5], v[20:21]
	s_nop 0
	v_pk_add_f32 v[4:5], v[22:23], v[4:5]
	s_nop 0
	v_cndmask_b32_e32 v4, v49, v4, vcc
	v_cmp_neq_f32_e32 vcc, s51, v54
	s_nop 1
	v_cndmask_b32_e32 v5, v49, v5, vcc
	v_cmp_ngt_f32_e32 vcc, -1.0, v54
	s_nop 1
	v_cndmask_b32_e32 v5, v50, v5, vcc
	v_cmp_ngt_f32_e32 vcc, -1.0, v53
	s_nop 1
	v_cndmask_b32_e32 v4, v50, v4, vcc
	v_cmp_neq_f32_e32 vcc, -1.0, v53
	s_nop 1
	v_cndmask_b32_e32 v4, v51, v4, vcc
	v_cmp_neq_f32_e32 vcc, -1.0, v54
	s_nop 1
	v_cndmask_b32_e32 v5, v51, v5, vcc
	v_cmp_lt_f32_e64 vcc, |v53|, s53
	v_cndmask_b32_e64 v5, v5, v54, s[36:37]
	s_nop 0
	v_cndmask_b32_e32 v4, v4, v53, vcc
	v_pk_add_f32 v[0:1], v[0:1], v[4:5] neg_lo:[0,1] neg_hi:[0,1]
	v_fmamk_f32 v4, v6, 0x3a800000, v48
	v_rsq_f32_e32 v4, v4
	s_nop 0
	v_fma_f32 v4, v2, v4, v52
	v_min_f32_e32 v2, 0, v4
	v_mul_f32_e64 v4, |v4|, s47
	v_exp_f32_e32 v53, v4
	s_nop 0
	v_add_f32_e32 v6, 1.0, v53
	v_add_f32_e32 v4, -1.0, v6
	v_sub_f32_e32 v5, v4, v6
	v_add_f32_e32 v5, 1.0, v5
	v_sub_f32_e32 v4, v53, v4
	v_add_f32_e32 v20, v4, v5
	v_frexp_mant_f32_e32 v4, v6
	v_cmp_gt_f32_e32 vcc, s49, v4
	v_cvt_f64_f32_e32 v[4:5], v6
	v_frexp_exp_i32_f64_e32 v4, v[4:5]
	v_subbrev_co_u32_e32 v36, vcc, 0, v4, vcc
	v_sub_u32_e32 v5, 0, v36
	v_ldexp_f32 v4, v6, v5
	v_ldexp_f32 v6, v20, v5
	v_fmamk_f32 v5, v7, 0x3a800000, v48
	v_rsq_f32_e32 v5, v5
	s_nop 0
	v_fmac_f32_e32 v52, v3, v5
	v_mul_f32_e64 v5, |v52|, s47
	v_min_f32_e32 v3, 0, v52
	v_exp_f32_e32 v52, v5
	s_nop 0
	v_add_f32_e32 v5, 1.0, v52
	v_add_f32_e32 v7, -1.0, v5
	v_sub_f32_e32 v20, v7, v5
	v_add_f32_e32 v20, 1.0, v20
	v_sub_f32_e32 v7, v52, v7
	v_add_f32_e32 v7, v7, v20
	v_frexp_mant_f32_e32 v20, v5
	v_cmp_gt_f32_e32 vcc, s49, v20
	v_cvt_f64_f32_e32 v[20:21], v5
	v_frexp_exp_i32_f64_e32 v20, v[20:21]
	v_subbrev_co_u32_e32 v37, vcc, 0, v20, vcc
	v_sub_u32_e32 v20, 0, v37
	v_ldexp_f32 v5, v5, v20
	v_ldexp_f32 v7, v7, v20
	v_pk_add_f32 v[20:21], v[4:5], 1.0 op_sel_hi:[1,0]
	v_pk_add_f32 v[28:29], v[4:5], -1.0 op_sel_hi:[1,0]
; __device__ __forceinline__ void fl_phase(const bf16* H, const bf16* Wfl, const float* bfv, const float* rowss, const float* biasp, float* logf, int G) {
;     ...
;         for (int r = 0; r < 4; ++r) { const float z = acc[r] * __builtin_amdgcn_rsqf(rq[r] * (1.0f / 1024.0f) + EPSN) + bias; o[r] = fminf(z, 0.f) - log1pf(__expf(-fabsf(z))); }
	v_pk_add_f32 v[22:23], v[20:21], -1.0 op_sel_hi:[1,0]
	v_pk_add_f32 v[30:31], v[28:29], 1.0 op_sel_hi:[1,0]
	v_pk_add_f32 v[22:23], v[4:5], v[22:23] neg_lo:[0,1] neg_hi:[0,1]
	v_pk_add_f32 v[4:5], v[4:5], v[30:31] neg_lo:[0,1] neg_hi:[0,1]
	v_pk_add_f32 v[22:23], v[6:7], v[22:23]
	v_pk_add_f32 v[4:5], v[6:7], v[4:5]
	v_pk_add_f32 v[24:25], v[20:21], v[22:23]
	v_pk_add_f32 v[6:7], v[28:29], v[4:5]
	v_rcp_f32_e32 v26, v24
	v_rcp_f32_e32 v27, v25
	v_pk_add_f32 v[20:21], v[24:25], v[20:21] neg_lo:[0,1] neg_hi:[0,1]
	v_pk_add_f32 v[28:29], v[6:7], v[28:29] neg_lo:[0,1] neg_hi:[0,1]
	v_pk_add_f32 v[20:21], v[22:23], v[20:21] neg_lo:[0,1] neg_hi:[0,1]
	v_pk_mul_f32 v[22:23], v[6:7], v[26:27]
	v_pk_add_f32 v[4:5], v[4:5], v[28:29] neg_lo:[0,1] neg_hi:[0,1]
	v_pk_mul_f32 v[28:29], v[24:25], v[22:23]
	v_cmp_neq_f32_e32 vcc, s51, v53
	v_pk_fma_f32 v[30:31], v[22:23], v[24:25], v[28:29] neg_lo:[0,0,1] neg_hi:[0,0,1]
	v_cmp_lt_f32_e64 s[36:37], |v52|, s53
	v_pk_fma_f32 v[30:31], v[22:23], v[20:21], v[30:31]
	s_nop 0
	v_pk_add_f32 v[32:33], v[28:29], v[30:31]
	s_nop 0
	v_pk_add_f32 v[34:35], v[6:7], v[32:33] neg_lo:[0,1] neg_hi:[0,1]
	v_pk_add_f32 v[28:29], v[32:33], v[28:29] neg_lo:[0,1] neg_hi:[0,1]
	v_pk_add_f32 v[6:7], v[6:7], v[34:35] neg_lo:[0,1] neg_hi:[0,1]
	s_nop 0
	v_pk_add_f32 v[6:7], v[6:7], v[32:33] neg_lo:[0,1] neg_hi:[0,1]
	s_nop 0
	v_pk_add_f32 v[4:5], v[4:5], v[6:7]
	v_pk_add_f32 v[6:7], v[28:29], v[30:31] neg_lo:[0,1] neg_hi:[0,1]
	s_nop 0
	v_pk_add_f32 v[4:5], v[6:7], v[4:5]
	s_nop 0
	v_pk_add_f32 v[6:7], v[34:35], v[4:5]
	s_nop 0
	v_pk_mul_f32 v[28:29], v[26:27], v[6:7]
	s_nop 0
	v_pk_mul_f32 v[30:31], v[24:25], v[28:29]
	s_nop 0
	v_pk_fma_f32 v[24:25], v[28:29], v[24:25], v[30:31] neg_lo:[0,0,1] neg_hi:[0,0,1]
	s_nop 0
	v_pk_fma_f32 v[20:21], v[28:29], v[20:21], v[24:25]
	v_pk_add_f32 v[24:25], v[34:35], v[6:7] neg_lo:[0,1] neg_hi:[0,1]
	s_nop 0
	v_pk_add_f32 v[4:5], v[4:5], v[24:25]
	v_pk_add_f32 v[24:25], v[30:31], v[20:21]
	s_nop 0
	v_pk_add_f32 v[32:33], v[6:7], v[24:25] neg_lo:[0,1] neg_hi:[0,1]
	v_pk_add_f32 v[30:31], v[24:25], v[30:31] neg_lo:[0,1] neg_hi:[0,1]
	v_pk_add_f32 v[6:7], v[6:7], v[32:33] neg_lo:[0,1] neg_hi:[0,1]
	s_nop 0
	v_pk_add_f32 v[6:7], v[6:7], v[24:25] neg_lo:[0,1] neg_hi:[0,1]
	s_nop 0
	v_pk_add_f32 v[4:5], v[4:5], v[6:7]
	v_pk_add_f32 v[6:7], v[30:31], v[20:21] neg_lo:[0,1] neg_hi:[0,1]
	s_nop 0
	v_pk_add_f32 v[4:5], v[6:7], v[4:5]
	v_pk_add_f32 v[6:7], v[22:23], v[28:29]
	v_pk_add_f32 v[4:5], v[32:33], v[4:5]
	v_pk_add_f32 v[20:21], v[6:7], v[22:23] neg_lo:[0,1] neg_hi:[0,1]
	v_pk_mul_f32 v[4:5], v[26:27], v[4:5]
	v_pk_add_f32 v[20:21], v[28:29], v[20:21] neg_lo:[0,1] neg_hi:[0,1]
	s_nop 0
	v_pk_add_f32 v[4:5], v[20:21], v[4:5]
	s_nop 0
	v_pk_add_f32 v[20:21], v[6:7], v[4:5]
	s_nop 0
	v_pk_mul_f32 v[22:23], v[20:21], v[20:21]
	v_pk_add_f32 v[6:7], v[20:21], v[6:7] neg_lo:[0,1] neg_hi:[0,1]
	v_pk_fma_f32 v[24:25], v[22:23], s[46:47], v[18:19] op_sel_hi:[1,0,0]
	v_pk_add_f32 v[4:5], v[4:5], v[6:7] neg_lo:[0,1] neg_hi:[0,1]
	v_ldexp_f32 v6, v20, 1
	v_pk_fma_f32 v[24:25], v[22:23], v[24:25], s[48:49] op_sel_hi:[1,1,0]
	v_ldexp_f32 v7, v21, 1
	v_pk_mul_f32 v[20:21], v[20:21], v[22:23]
	v_cvt_f32_i32_e32 v23, v37
	v_cvt_f32_i32_e32 v22, v36
	v_pk_mul_f32 v[20:21], v[20:21], v[24:25]
	v_ldexp_f32 v27, v5, 1
	v_pk_add_f32 v[24:25], v[6:7], v[20:21]
	v_pk_mul_f32 v[28:29], v[22:23], s[50:51] op_sel_hi:[1,0]
	v_pk_add_f32 v[6:7], v[24:25], v[6:7] neg_lo:[0,1] neg_hi:[0,1]
	v_pk_fma_f32 v[30:31], v[22:23], s[50:51], v[28:29] op_sel_hi:[1,0,1] neg_lo:[0,0,1] neg_hi:[0,0,1]
	v_pk_add_f32 v[6:7], v[20:21], v[6:7] neg_lo:[0,1] neg_hi:[0,1]
; __device__ __forceinline__ void fl_phase(const bf16* H, const bf16* Wfl, const float* bfv, const float* rowss, const float* biasp, float* logf, int G) {
;     ...
; #pragma unroll
;         for (int r = 0; r < 4; ++r) { const float z = acc[r] * __builtin_amdgcn_rsqf(rq[r] * (1.0f / 1024.0f) + EPSN) + bias; o[r] = fminf(z, 0.f) - log1pf(__expf(-fabsf(z))); }
;         *(f32x4*)(logf + (size_t)(bb * 16 + li) * SEQL + t) = o;
	v_pk_fma_f32 v[22:23], v[22:23], s[52:53], v[30:31] op_sel_hi:[1,0,1]
	v_ldexp_f32 v4, v4, 1
	v_mov_b32_e32 v20, v28
	v_mov_b32_e32 v21, v7
	v_mov_b32_e32 v26, v22
	v_mov_b32_e32 v5, v27
	v_pk_add_f32 v[20:21], v[20:21], v[26:27]
	v_pk_add_f32 v[26:27], v[4:5], v[6:7]
	v_mov_b32_e32 v7, v25
	v_mov_b32_e32 v5, v27
	v_pk_add_f32 v[30:31], v[28:29], v[22:23]
	v_pk_add_f32 v[4:5], v[4:5], v[6:7]
	v_pk_add_f32 v[6:7], v[24:25], v[26:27]
	v_mov_b32_e32 v40, v24
	v_pk_add_f32 v[32:33], v[30:31], v[6:7]
	v_mov_b32_e32 v38, v6
	v_mov_b32_e32 v39, v33
	v_mov_b32_e32 v41, v31
	v_pk_add_f32 v[38:39], v[38:39], v[40:41] neg_lo:[0,1] neg_hi:[0,1]
	v_mov_b32_e32 v34, v32
	v_mov_b32_e32 v35, v31
	v_mov_b32_e32 v36, v30
	v_mov_b32_e32 v37, v29
	v_mov_b32_e32 v40, v30
	v_mov_b32_e32 v41, v33
	v_mov_b32_e32 v29, v39
	v_pk_add_f32 v[34:35], v[34:35], v[36:37] neg_lo:[0,1] neg_hi:[0,1]
	v_mov_b32_e32 v36, v6
	v_mov_b32_e32 v37, v23
	v_pk_add_f32 v[28:29], v[40:41], v[28:29] neg_lo:[0,1] neg_hi:[0,1]
	v_pk_add_f32 v[36:37], v[36:37], v[34:35] neg_lo:[0,1] neg_hi:[0,1]
	v_mov_b32_e32 v40, v28
	v_mov_b32_e32 v41, v35
	v_mov_b32_e32 v42, v32
	v_mov_b32_e32 v43, v7
	v_mov_b32_e32 v35, v25
	v_pk_add_f32 v[40:41], v[22:23], v[40:41] neg_lo:[0,1] neg_hi:[0,1]
	v_pk_add_f32 v[34:35], v[42:43], v[34:35] neg_lo:[0,1] neg_hi:[0,1]
	v_mov_b32_e32 v23, v31
	v_pk_add_f32 v[20:21], v[20:21], v[34:35] neg_lo:[0,1] neg_hi:[0,1]
	v_pk_add_f32 v[22:23], v[22:23], v[28:29] neg_lo:[0,1] neg_hi:[0,1]
	v_pk_add_f32 v[4:5], v[4:5], v[38:39] neg_lo:[0,1] neg_hi:[0,1]
	v_pk_add_f32 v[6:7], v[6:7], v[24:25] neg_lo:[0,1] neg_hi:[0,1]
	v_pk_add_f32 v[24:25], v[4:5], v[22:23]
	v_mov_b32_e32 v23, v37
	v_mov_b32_e32 v5, v21
	v_pk_add_f32 v[6:7], v[26:27], v[6:7] neg_lo:[0,1] neg_hi:[0,1]
	v_pk_add_f32 v[26:27], v[36:37], v[20:21]
	v_pk_add_f32 v[4:5], v[22:23], v[4:5]
	v_mov_b32_e32 v20, v24
	v_pk_add_f32 v[4:5], v[4:5], v[40:41] neg_lo:[0,1] neg_hi:[0,1]
	v_mov_b32_e32 v21, v27
	v_pk_add_f32 v[20:21], v[20:21], v[4:5] neg_lo:[0,1] neg_hi:[0,1]
	v_pk_add_f32 v[4:5], v[6:7], v[4:5] neg_lo:[0,1] neg_hi:[0,1]
	v_pk_add_f32 v[20:21], v[22:23], v[20:21] neg_lo:[0,1] neg_hi:[0,1]
	v_pk_add_f32 v[6:7], v[26:27], v[24:25]
	v_pk_add_f32 v[4:5], v[4:5], v[20:21]
	v_pk_add_f32 v[20:21], v[32:33], v[6:7]
	s_nop 0
	v_pk_add_f32 v[22:23], v[20:21], v[32:33] neg_lo:[0,1] neg_hi:[0,1]
	s_nop 0
	v_pk_add_f32 v[6:7], v[6:7], v[22:23] neg_lo:[0,1] neg_hi:[0,1]
	s_nop 0
	v_pk_add_f32 v[4:5], v[4:5], v[6:7]
	v_bitop3_b32 v6, v8, s14, v47 bitop3:0xc8
	v_pk_add_f32 v[4:5], v[20:21], v[4:5]
	s_movk_i32 s14, 0x3ff
	v_cndmask_b32_e32 v4, v49, v4, vcc
	v_cmp_neq_f32_e32 vcc, s51, v52
	v_lshlrev_b32_e32 v8, 2, v6
	s_nop 0
	v_cndmask_b32_e32 v5, v49, v5, vcc
	v_cmp_ngt_f32_e32 vcc, -1.0, v52
	s_nop 1
	v_cndmask_b32_e32 v5, v50, v5, vcc
	v_cmp_ngt_f32_e32 vcc, -1.0, v53
	s_nop 1
	v_cndmask_b32_e32 v4, v50, v4, vcc
	v_cmp_neq_f32_e32 vcc, -1.0, v53
	s_nop 1
	v_cndmask_b32_e32 v4, v51, v4, vcc
	v_cmp_neq_f32_e32 vcc, -1.0, v52
	s_nop 1
	v_cndmask_b32_e32 v5, v51, v5, vcc
	v_cmp_lt_f32_e64 vcc, |v53|, s53
	v_cndmask_b32_e64 v5, v5, v52, s[36:37]
	s_nop 0
	v_cndmask_b32_e32 v4, v4, v53, vcc
	v_pk_add_f32 v[2:3], v[2:3], v[4:5] neg_lo:[0,1] neg_hi:[0,1]
	v_lshl_or_b32 v4, v15, 4, v45
	v_ashrrev_i32_e32 v5, 31, v4
	v_lshlrev_b64 v[4:5], 15, v[4:5]
	v_lshl_add_u64 v[4:5], s[0:1], 0, v[4:5]
	v_cmp_lt_i32_e32 vcc, s14, v44
	v_lshl_add_u64 v[4:5], v[4:5], 0, v[8:9]
	s_or_b64 s[40:41], vcc, s[40:41]
	global_store_dwordx4 v[4:5], v[0:3], off sc1
	s_andn2_b64 exec, exec, s[40:41]
	s_cbranch_execnz .LBB0_619

; #define PG8_STAGE(bufoff, gbase, voff) do { _Pragma("unroll") for (int _i = 0; _i < 2; ++_i) \
;         __builtin_amdgcn_global_load_lds((const unsigned*)((const char*)(gbase) + (voff)[_i]), (PG8_LAS unsigned*)(lds + (bufoff) + ldsw + _i * 8192), 16, 0, 0); } while (0)
; #define PG8_WAIT_V(n) asm volatile("s_waitcnt vmcnt(" #n ")" ::: "memory")
; #define PG8_BAR __builtin_amdgcn_s_barrier()
; template <class Epi, class Sched, bool ALIGN_EPI = false, bool SP2 = false>
; __device__ __forceinline__ void gemm_phase(PG8_LAS unsigned char* lds, const Gemm g, const Sched& S, const Epi& E) {
;     ...
;         PG8_STAGE(PG8_SB(0, 0), cB, voffB); PG8_STAGE(PG8_SB(0, 1), cB + hstep, voffB); PG8_STAGE(PG8_SA(0, 0), cA, voffA); PG8_STAGE(PG8_SA(0, 1), cA + hstep, voffA);
;         if (wr == 1) PG8_BAR;
;         PG8_WAIT_V(2); PG8_BAR;
;         PG8_STAGE(PG8_SB(1, 0), cB + kstep, voffB); PG8_STAGE(PG8_SA(1, 0), cA + kstep, voffA); PG8_STAGE(PG8_SB(1, 1), cB + hstep + kstep, voffB);
;         PG8_WAIT_V(6); PG8_BAR;
; __global__ void __launch_bounds__(NTHR, 2) fwd_megakernel(Args args) {
;     ...
;         fl_phase(H, (const bf16*)(ws + WS_W1IN) + (size_t)4096 * D, args.in[12], (const float*)(ws + WS_ROWSS), (const float*)(ws + WS_BIAS1), (float*)(ws + WS_LOGF), G);
;       pg8::Gemm g{H, (const bf16*)(ws + WS_W1IN), M, N1, D}; pg8::StaticOrder S; S.init(M, N1, G, (int)blockIdx.x);
;       pg8::EpiOdd E{attn_body::C2, P0, args.in[13], args.in[14], (const float*)(ws + WS_BIAS1), (const float*)(ws + WS_ROWSS)};
;       pg8::gemm_phase<pg8::EpiOdd, pg8::StaticOrder, true, true>(lds, g, S, E);
.LBB0_627:
	s_mov_b64 s[46:47], 0x80
	s_and_b32 s77, s17, 3
	s_add_i32 m0, s61, 0x18000
	v_lshl_add_u64 v[6:7], v[6:7], 0, s[46:47]
	s_lshl_b32 s17, s18, 13
	s_lshl_b32 s19, s77, 5
	s_lshl_b32 s24, s77, 12
	s_waitcnt vmcnt(2)
	s_barrier
	s_and_saveexec_b64 s[100:101], s[92:93]
	s_cbranch_execz .Lp8_sig_done
	v_mov_b32_e32 v250, 0
	v_mov_b32_e32 v251, 1
	global_atomic_add v250, v251, s[10:11] offset:3072
.Lp8_sig_done:
	s_mov_b64 exec, s[100:101]
	global_load_lds_dwordx4 v[6:7], off
	v_lshl_add_u64 v[2:3], v[2:3], 0, s[46:47]
	s_add_i32 m0, s61, 0x1a000
	s_add_i32 s78, s61, 0x8000
	s_add_i32 s79, s61, 0xa000
	global_load_lds_dwordx4 v[2:3], off
	v_lshl_add_u64 v[0:1], v[0:1], 0, s[46:47]
	s_mov_b32 m0, s78
	s_add_u32 s14, s40, 0x40080
	global_load_lds_dwordx4 v[0:1], off
	v_lshl_add_u64 v[0:1], v[4:5], 0, s[46:47]
	s_mov_b32 m0, s79
	s_addc_u32 s15, s41, 0
	global_load_lds_dwordx4 v[0:1], off
	s_add_i32 m0, s61, 0x1c000
	v_lshl_add_u64 v[0:1], s[14:15], 0, v[162:163]
	global_load_lds_dwordx4 v[0:1], off
	v_lshl_add_u64 v[0:1], s[14:15], 0, v[166:167]
	s_add_i32 m0, s61, 0x1e000
	s_cmpk_lt_u32 s16, 0x100
	global_load_lds_dwordx4 v[0:1], off
	v_lshrrev_b32_e32 v1, 1, v8
	v_and_b32_e32 v170, 24, v1
	v_and_b32_e32 v0, 15, v8
	v_lshlrev_b32_e32 v1, 1, v170
	v_lshl_or_b32 v171, s18, 6, v0
	v_lshl_or_b32 v0, v0, 6, v1
	v_lshlrev_b32_e32 v1, 2, v8
	v_and_b32_e32 v1, 32, v1
	v_bitop3_b32 v2, v0, s17, v1 bitop3:0xde
	v_bitop3_b32 v197, v0, s24, v1 bitop3:0xde
	v_lshlrev_b32_e32 v0, 14, v9
	v_and_b32_e32 v0, 0xffff8000, v0
	v_lshl_add_u32 v0, v10, 11, v0
	v_and_b32_e32 v1, 1, v9
	v_lshl_or_b32 v0, v1, 6, v0
	v_lshl_add_u32 v176, v11, 1, v0
	v_lshlrev_b32_e32 v0, 14, v12
	v_and_b32_e32 v0, 0xffff8000, v0
	s_waitcnt vmcnt(6)
	v_lshl_add_u32 v0, v13, 11, v0
	v_and_b32_e32 v1, 1, v12
	s_cselect_b64 s[48:49], -1, 0
	v_lshlrev_b32_e32 v168, 2, v170
	v_lshl_or_b32 v0, v1, 6, v0
	s_add_i32 s80, 0, 0x10000
	s_add_i32 s81, 0, 0x14000
	v_lshl_add_u64 v[172:173], s[64:65], 0, v[168:169]
	v_lshl_add_u64 v[174:175], s[62:63], 0, v[168:169]
	v_mov_b32_e32 v177, v169
	v_lshl_add_u32 v178, v14, 1, v0
	v_mov_b32_e32 v179, v169
	v_mov_b64_e32 v[180:181], 0x400
	v_mov_b64_e32 v[182:183], 0x3ff
	v_add_u32_e32 v198, s80, v197
	v_add_u32_e32 v199, s81, v197
	v_add_u32_e32 v200, 0, v2
	s_mov_b32 s50, 0x3e38aa3b
	s_lshl_b32 s82, s19, 2
	v_lshlrev_b32_e32 v168, 2, v170
	v_mov_b32_e32 v201, 0x358637bd
	s_barrier
	s_branch .LBB0_630

; __device__ __forceinline__ unsigned xb_ld(unsigned* p)              { return __hip_atomic_load(p, __ATOMIC_RELAXED, __HIP_MEMORY_SCOPE_AGENT); }
; __device__ __forceinline__ unsigned xb_add(unsigned* p, unsigned v) { return __hip_atomic_fetch_add(p, v, __ATOMIC_RELAXED, __HIP_MEMORY_SCOPE_AGENT); }
; #define XB_SPIN(cond, bar) do { unsigned _sp = 0; while (cond) { __builtin_amdgcn_s_sleep(1); \
;     if ((++_sp & 255u) == 0u) { if (xb_ld(&(bar)[XB_TMO])) break; if (_sp > XB_SPIN_CAP) { atomicAdd(&(bar)[XB_TMO], 1u); break; } } } } while (0)
; #define GSYNC() do { xcd_barrier(xbar); xcd_barrier(xbar); } while (0)
; #define GSYNC() xcd_barrier(xbar)
; #define REP(p) for (int rep_ = 0; rep_ < (((PROBE_MASK >> (p)) & 1) ? 2 : 1); ++rep_)
; __device__ __forceinline__ void xcd_barrier(const XcdBarrier& b) {
;     asm volatile("s_waitcnt vmcnt(0)" ::: "memory");
;     __syncthreads();
;     if (threadIdx.x == 0) {
;         unsigned* bar = b.bar;
;         __builtin_amdgcn_s_waitcnt(0);
;         unsigned nloc = b.st[0], nx = b.st[1];
;         if (nloc == 0u) { xcd_barrier_complete(bar, b.x, nloc, nx); b.st[0] = nloc; b.st[1] = nx; }
;         const unsigned old = xb_add(&bar[XB_XSUB(b.x)], 1u);
;         const unsigned gen = old / nloc;
;         if (old + 1u == (gen + 1u) * nloc) {
;             __builtin_amdgcn_fence(__ATOMIC_RELEASE, "agent");
;             asm volatile("s_waitcnt vmcnt(0)" ::: "memory");
;             const unsigned og = xb_add(&bar[XB_TOP], 1u);
;             const unsigned tg = og / nx;
;             if (og + 1u == (tg + 1u) * nx) xb_add(&bar[XB_TOPGEN], 1u);
;             else XB_SPIN(xb_ld(&bar[XB_TOPGEN]) == tg, bar);
;             __builtin_amdgcn_fence(__ATOMIC_ACQUIRE, "agent");
;             xb_add(&bar[XB_XGEN(b.x)], 1u);
;             asm volatile("s_waitcnt vmcnt(0)" ::: "memory");
;         } else {
;             XB_SPIN(xb_ld(&bar[XB_XGEN(b.x)]) == gen, bar);
;             __builtin_amdgcn_fence(__ATOMIC_ACQUIRE, "agent");
;             asm volatile("s_waitcnt vmcnt(0)" ::: "memory");
;         }
;     }
;     __syncthreads();
; }
; __global__ void __launch_bounds__(NTHR, 2) fwd_megakernel(Args args) {
;     ...
;     GSYNC(); }
;     REP(9) { cumf_phase(lds, (const float*)(ws + WS_LOGF), (float*)(ws + WS_CUMF), G);
;     GSYNC(); }
.LBB0_684:
	s_waitcnt vmcnt(0)
	s_cmp_gt_i32 s91, 31
	s_cbranch_scc1 .Lp9_nowait
	s_and_saveexec_b64 s[100:101], s[92:93]
	s_cbranch_execz .Lp9_polled
	v_mov_b32_e32 v250, 0
.Lp9_poll:
	global_load_dword v251, v250, s[10:11] offset:3072 sc1
	s_waitcnt vmcnt(0)
	v_cmp_gt_u32_e32 vcc, s6, v251
	s_nop 1
	s_cbranch_vccz .Lp9_pollend
	s_sleep 1
	s_branch .Lp9_poll

; #define LAS __attribute__((address_space(3)))
; __device__ __forceinline__ unsigned xb_ld(unsigned* p)              { return __hip_atomic_load(p, __ATOMIC_RELAXED, __HIP_MEMORY_SCOPE_AGENT); }
; __device__ __forceinline__ unsigned xb_add(unsigned* p, unsigned v) { return __hip_atomic_fetch_add(p, v, __ATOMIC_RELAXED, __HIP_MEMORY_SCOPE_AGENT); }
; #define XB_SPIN(cond, bar) do { unsigned _sp = 0; while (cond) { __builtin_amdgcn_s_sleep(1); \
;     if ((++_sp & 255u) == 0u) { if (xb_ld(&(bar)[XB_TMO])) break; if (_sp > XB_SPIN_CAP) { atomicAdd(&(bar)[XB_TMO], 1u); break; } } } } while (0)
; __device__ __forceinline__ void cumf_phase(LAS unsigned char* lds, const float* logf, float* cumf, int G) {
;     int tid = threadIdx.x; asm volatile("" : "+v"(tid)); const int lane = tid & 63, wave = tid >> 6;
;     LAS float* wt = (LAS float*)lds;
;     for (int bh = blockIdx.x; bh < 32; bh += G) {
;         const f32x4* src = (const f32x4*)(logf + (size_t)bh * SEQL + 16 * tid);
;         f32x4 v[4]; float run = 0.f;
; #pragma unroll
;         for (int j = 0; j < 4; ++j) { v[j] = src[j]; v[j].x += run; v[j].y += v[j].x; v[j].z += v[j].y; v[j].w += v[j].z; run = v[j].w; }
;         float inc = run;
; #pragma unroll
;         for (int o = 1; o < 64; o <<= 1) { const float n = __shfl_up(inc, o); if (lane >= o) inc += n; }
; __device__ __forceinline__ void xcd_barrier(const XcdBarrier& b) {
;     ...
;         const unsigned old = xb_add(&bar[XB_XSUB(b.x)], 1u);
;         const unsigned gen = old / nloc;
;         if (old + 1u == (gen + 1u) * nloc) {
;             __builtin_amdgcn_fence(__ATOMIC_RELEASE, "agent");
;             asm volatile("s_waitcnt vmcnt(0)" ::: "memory");
;             const unsigned og = xb_add(&bar[XB_TOP], 1u);
;             const unsigned tg = og / nx;
;             if (og + 1u == (tg + 1u) * nx) xb_add(&bar[XB_TOPGEN], 1u);
;             else XB_SPIN(xb_ld(&bar[XB_TOPGEN]) == tg, bar);
;             __builtin_amdgcn_fence(__ATOMIC_ACQUIRE, "agent");
;             xb_add(&bar[XB_XGEN(b.x)], 1u);
;             asm volatile("s_waitcnt vmcnt(0)" ::: "memory");
;         } else {
;             XB_SPIN(xb_ld(&bar[XB_XGEN(b.x)]) == gen, bar);
;             __builtin_amdgcn_fence(__ATOMIC_ACQUIRE, "agent");
;             asm volatile("s_waitcnt vmcnt(0)" ::: "memory");
;         }
.Lp9_polled:
	s_mov_b64 exec, s[100:101]
	s_barrier
.Lp9_nowait:
	s_cmp_gt_i32 s91, 31
	v_mov_b32_e32 v0, v216
	s_waitcnt lgkmcnt(0)
	s_cbranch_scc1 .LBB0_752
	v_add_u32_e32 v6, -1, v208
	v_cmp_lt_i32_e64 s[38:39], v6, v217
	v_ashrrev_i32_e32 v4, 6, v0
	v_and_b32_e32 v5, 63, v0
	v_cndmask_b32_e64 v6, v6, v208, s[38:39]
	v_lshlrev_b32_e32 v22, 2, v6
	v_add_u32_e32 v6, -2, v208
	v_cmp_lt_i32_e64 s[40:41], v6, v217
	v_lshlrev_b32_e32 v0, 4, v0
	v_ashrrev_i32_e32 v1, 31, v0
	v_cndmask_b32_e64 v6, v6, v208, s[40:41]
	v_lshlrev_b32_e32 v23, 2, v6
	v_add_u32_e32 v6, -4, v208
	v_cmp_lt_i32_e64 s[42:43], v6, v217
	v_lshlrev_b64 v[2:3], 2, v[0:1]
	v_lshl_add_u64 v[0:1], s[0:1], 0, v[2:3]
	v_cndmask_b32_e64 v6, v6, v208, s[42:43]
	v_lshlrev_b32_e32 v24, 2, v6
	v_add_u32_e32 v6, -8, v208
	v_cmp_lt_i32_e64 s[44:45], v6, v217
	v_lshl_add_u64 v[2:3], s[10:11], 0, v[2:3]
	s_mov_b64 s[0:1], 0x1700000
	v_cndmask_b32_e64 v6, v6, v208, s[44:45]
	v_lshlrev_b32_e32 v25, 2, v6
	v_add_u32_e32 v6, -16, v208
	v_cmp_lt_i32_e64 s[46:47], v6, v217
	v_and_b32_e32 v28, 7, v4
	v_cmp_eq_u32_e32 vcc, 63, v5
	v_cndmask_b32_e64 v6, v6, v208, s[46:47]
	v_lshlrev_b32_e32 v26, 2, v6
	v_subrev_u32_e32 v6, 32, v208
	v_cmp_lt_i32_e64 s[48:49], v6, v217
	v_lshl_add_u32 v21, v4, 2, 0
	v_cmp_lt_i32_e64 s[36:37], 0, v4
	v_cndmask_b32_e64 v6, v6, v208, s[48:49]
	v_lshl_add_u64 v[2:3], v[2:3], 0, s[0:1]
	v_cmp_eq_u32_e64 s[38:39], 0, v5
	v_cmp_gt_u32_e64 s[40:41], 2, v5
	v_cmp_gt_u32_e64 s[42:43], 4, v5
	v_cmp_gt_u32_e64 s[44:45], 8, v5
	v_cmp_gt_u32_e64 s[46:47], 16, v5
	v_lshlrev_b32_e32 v27, 2, v6
	v_cmp_gt_u32_e64 s[48:49], 32, v5
	v_cmp_lt_u32_e64 s[50:51], 7, v4
	v_and_b32_e32 v29, 0x7ffffff8, v4
	v_cmp_ne_u32_e64 s[52:53], 0, v28
	s_mov_b32 s0, s91
	s_branch .LBB0_740

; __device__ __forceinline__ unsigned xb_add(unsigned* p, unsigned v) { return __hip_atomic_fetch_add(p, v, __ATOMIC_RELAXED, __HIP_MEMORY_SCOPE_AGENT); }
; __device__ __forceinline__ void xcd_barrier(const XcdBarrier& b) {
;     ...
;             __builtin_amdgcn_fence(__ATOMIC_ACQUIRE, "agent");
;             xb_add(&bar[XB_XGEN(b.x)], 1u);
;             asm volatile("s_waitcnt vmcnt(0)" ::: "memory");
.LBB0_801:
	s_or_b64 exec, exec, s[4:5]
	s_mov_b64 s[4:5], exec
	v_mbcnt_lo_u32_b32 v0, s4, 0
	v_mbcnt_hi_u32_b32 v0, s5, v0
	v_cmp_eq_u32_e32 vcc, 0, v0
	s_waitcnt vmcnt(0)
	buffer_inv sc1
	s_and_saveexec_b64 s[18:19], vcc
	s_cbranch_execz .LBB0_803
	s_bcnt1_i32_b64 s4, s[4:5]
	v_mov_b32_e32 v0, 0
	v_mov_b32_e32 v1, s4
.LBB0_803:
	s_or_b64 exec, exec, s[18:19]
	s_waitcnt vmcnt(0)

; __device__ __forceinline__ unsigned xb_add(unsigned* p, unsigned v) { return __hip_atomic_fetch_add(p, v, __ATOMIC_RELAXED, __HIP_MEMORY_SCOPE_AGENT); }
; __device__ __forceinline__ void xcd_barrier(const XcdBarrier& b) {
;     ...
;             __builtin_amdgcn_fence(__ATOMIC_ACQUIRE, "agent");
;             xb_add(&bar[XB_XGEN(b.x)], 1u);
;             asm volatile("s_waitcnt vmcnt(0)" ::: "memory");
.LBB0_975:
	s_or_b64 exec, exec, s[4:5]
	s_mov_b64 s[4:5], exec
	v_mbcnt_lo_u32_b32 v0, s4, 0
	v_mbcnt_hi_u32_b32 v0, s5, v0
	v_cmp_eq_u32_e32 vcc, 0, v0
	s_waitcnt vmcnt(0)
	buffer_inv sc1
	s_and_saveexec_b64 s[14:15], vcc
	s_cbranch_execz .LBB0_977
	s_bcnt1_i32_b64 s4, s[4:5]
	v_mov_b32_e32 v0, 0
	v_mov_b32_e32 v1, s4
.LBB0_977:
	s_or_b64 exec, exec, s[14:15]
	s_waitcnt vmcnt(0)
